# LN1/LN2/final row loops: gamma/beta loaded once before the loop (32 VGPRs) instead of four serialized load+wait pairs per row; loop-top wait no longer waits for store acks
# speedup vs baseline: 1.0127x; 1.0116x over previous
;   __device__ __forceinline__ unsigned char* W() const { return (unsigned char*)(GAS unsigned char*)ws; }
; __device__ __forceinline__ void ln_row_regs(f32x4 (&v)[4], const float* g, const float* bb, int lane) {
;     ...
;     const f32x4 gg = *(const f32x4*)(g + lane * 4 + i * 256), b4 = *(const f32x4*)(bb + lane * 4 + i * 256);
; __device__ __forceinline__ void ln_phase(const Params& p, const float* g, const float* bb, bf16_t* xb, int final_, int bid, int nb, const int tid) {
;   const int lane = tid & 63, wv = tid >> 6;
;   float* X = (float*)(p.W() + OFF_X);
;   f32x4 nx[4], nx2[4];
;   {
;     const int r0 = min(bid * 4 + wv, MT - 1), r1 = min(bid * 4 + wv + nb * 4, MT - 1);
; #pragma unroll
;     for (int i = 0; i < 4; ++i) nx[i] = *(const f32x4*)(X + (size_t)r0 * 1024 + lane * 4 + i * 256);
; #pragma unroll
;     for (int i = 0; i < 4; ++i) nx2[i] = *(const f32x4*)(X + (size_t)r1 * 1024 + lane * 4 + i * 256);
;   }
.LBB0_114:
	s_cmp_gt_i32 s56, 3
	s_mov_b64 s[2:3], -1
	s_cbranch_scc0 .LBB0_119
	v_ashrrev_i32_e32 v0, 6, v130
	v_readlane_b32 s2, v254, 61
	s_waitcnt vmcnt(4)
	s_nop 0
	v_lshl_add_u32 v50, s2, 2, v0
	s_movk_i32 s2, 0x4280
	v_cmp_gt_i32_e32 vcc, s2, v50
	s_and_saveexec_b64 s[2:3], vcc
	s_movk_i32 s23, 0x427f
	s_cbranch_execz .LBB0_118
	s_lshl_b32 s26, s66, 10
	s_ashr_i32 s27, s26, 31
	v_readlane_b32 s40, v254, 37
	s_lshl_b32 s24, s0, 2
	s_lshl_b64 s[26:27], s[26:27], 2
	v_readlane_b32 s44, v254, 41
	v_readlane_b32 s45, v254, 42
	s_add_u32 s34, s44, s26
	v_readlane_b32 s42, v254, 39
	s_addc_u32 s35, s45, s27
	v_readlane_b32 s43, v254, 40
	s_add_u32 s38, s42, s26
	v_lshlrev_b32_e32 v0, 2, v130
	s_addc_u32 s39, s43, s27
	v_ashrrev_i32_e32 v51, 31, v50
	v_readlane_b32 s26, v253, 25
	s_waitcnt vmcnt(0)
	v_and_b32_e32 v36, 0xfc, v0
	v_lshlrev_b64 v[0:1], 12, v[50:51]
	v_readlane_b32 s27, v253, 26
	v_lshlrev_b32_e32 v2, 2, v36
	v_and_b32_e32 v37, 64, v157
	v_lshl_add_u64 v[0:1], s[26:27], 0, v[0:1]
	v_lshl_add_u64 v[0:1], v[0:1], 0, v[2:3]
	global_load_dwordx4 v[32:35], v[0:1], off
	global_load_dwordx4 v[28:31], v[0:1], off offset:1024
	global_load_dwordx4 v[24:27], v[0:1], off offset:2048
	global_load_dwordx4 v[20:23], v[0:1], off offset:3072
	v_add_u32_e32 v0, s24, v50
	v_min_i32_e32 v0, 0x427f, v0
	v_ashrrev_i32_e32 v1, 31, v0
	v_lshlrev_b64 v[0:1], 12, v[0:1]
	v_lshl_add_u64 v[0:1], s[26:27], 0, v[0:1]
	v_lshl_add_u64 v[0:1], v[0:1], 0, v[2:3]
	global_load_dwordx4 v[8:11], v[0:1], off offset:3072
	global_load_dwordx4 v[4:7], v[0:1], off offset:2048
	global_load_dwordx4 v[12:15], v[0:1], off offset:1024
	global_load_dwordx4 v[16:19], v[0:1], off
	v_add_u32_e32 v37, 64, v37
	v_xor_b32_e32 v38, 32, v157
	v_cmp_lt_i32_e32 vcc, v38, v37
	v_lshl_add_u64 v[0:1], s[26:27], 0, v[2:3]
	v_readlane_b32 s26, v253, 21
	v_cndmask_b32_e32 v38, v157, v38, vcc
	v_lshlrev_b32_e32 v68, 2, v38
	v_xor_b32_e32 v38, 16, v157
	v_cmp_lt_i32_e32 vcc, v38, v37
	v_lshl_add_u64 v[52:53], s[38:39], 0, v[2:3]
	v_lshl_add_u64 v[54:55], s[34:35], 0, v[2:3]
	v_cndmask_b32_e32 v38, v157, v38, vcc
	v_lshlrev_b32_e32 v69, 2, v38
	v_xor_b32_e32 v38, 8, v157
	v_cmp_lt_i32_e32 vcc, v38, v37
	v_lshlrev_b32_e32 v2, 1, v36
	v_readlane_b32 s27, v253, 22
	v_cndmask_b32_e32 v38, v157, v38, vcc
	v_lshlrev_b32_e32 v70, 2, v38
	v_xor_b32_e32 v38, 4, v157
	v_cmp_lt_i32_e32 vcc, v38, v37
	s_lshl_b32 s25, s0, 3
	v_lshl_add_u64 v[56:57], s[26:27], 0, v[2:3]
	v_cndmask_b32_e32 v38, v157, v38, vcc
	v_lshlrev_b32_e32 v71, 2, v38
	v_xor_b32_e32 v38, 2, v157
	v_cmp_lt_i32_e32 vcc, v38, v37
	s_mov_b64 s[34:35], 0
	v_readlane_b32 s41, v254, 38
	v_cndmask_b32_e32 v38, v157, v38, vcc
	v_lshlrev_b32_e32 v72, 2, v38
	v_xor_b32_e32 v38, 1, v157
	v_cmp_lt_i32_e32 vcc, v38, v37
	v_readlane_b32 s46, v254, 43
	v_readlane_b32 s47, v254, 44
	v_cndmask_b32_e32 v37, v157, v38, vcc
	v_lshlrev_b32_e32 v73, 2, v37
	v_readlane_b32 s48, v254, 45
	v_readlane_b32 s49, v254, 46
	v_readlane_b32 s50, v254, 47
	v_readlane_b32 s51, v254, 48
	v_readlane_b32 s52, v254, 49
	v_readlane_b32 s53, v254, 50
	v_readlane_b32 s54, v254, 51
	v_readlane_b32 s55, v254, 52
	s_waitcnt vmcnt(7)
	v_mov_b32_e32 v60, v33
	v_mov_b32_e32 v61, v34
	v_mov_b32_e32 v33, v35
	s_waitcnt vmcnt(6)
	v_mov_b32_e32 v58, v29
	v_mov_b32_e32 v59, v30
	v_mov_b32_e32 v29, v31
	s_waitcnt vmcnt(4)
	v_mov_b32_e32 v30, v20
	v_mov_b32_e32 v62, v21
	v_mov_b32_e32 v64, v22
	v_mov_b32_e32 v66, v23
	global_load_dwordx4 v[184:187], v[52:53], off
	global_load_dwordx4 v[188:191], v[52:53], off offset:1024
	global_load_dwordx4 v[192:195], v[52:53], off offset:2048
	global_load_dwordx4 v[196:199], v[52:53], off offset:3072
	global_load_dwordx4 v[210:213], v[54:55], off
	global_load_dwordx4 v[214:217], v[54:55], off offset:1024
	global_load_dwordx4 v[218:221], v[54:55], off offset:2048
	global_load_dwordx4 v[222:225], v[54:55], off offset:3072
; __device__ __forceinline__ unsigned pk2(float lo, float hi) { const f32x2_t v = {lo, hi}; const bf16x2_t b = __builtin_convertvector(v, bf16x2_t); return __builtin_bit_cast(unsigned, b); }
; __device__ __forceinline__ void ln_row_regs(f32x4 (&v)[4], const float* g, const float* bb, int lane) {
;   float s = 0.f;
; #pragma unroll
;   for (int i = 0; i < 4; ++i) s += (v[i][0] + v[i][1]) + (v[i][2] + v[i][3]);
;   const float mu = wave_sum(s) * (1.0f / 1024.0f);
;   float q = 0.f;
; #pragma unroll
;   for (int i = 0; i < 4; ++i) { const f32x4 d = v[i] - mu; q += (d[0] * d[0] + d[1] * d[1]) + (d[2] * d[2] + d[3] * d[3]); }
;   const float rs = rsqrtf(wave_sum(q) * (1.0f / 1024.0f) + 1e-5f);
; #pragma unroll
;   for (int i = 0; i < 4; ++i) {
;     const f32x4 gg = *(const f32x4*)(g + lane * 4 + i * 256), b4 = *(const f32x4*)(bb + lane * 4 + i * 256);
;     v[i] = (v[i] - mu) * rs * gg + b4;
;   }
; __device__ __forceinline__ void ln_phase(const Params& p, const float* g, const float* bb, bf16_t* xb, int final_, int bid, int nb, const int tid) {
;     ...
;   for (int row = bid * 4 + wv; row < MT; row += nb * 4) {
;     f32x4 v[4];
; #pragma unroll
;     for (int i = 0; i < 4; ++i) { v[i] = nx[i]; nx[i] = nx2[i]; }
;     {
;       const int rn = min(row + nb * 8, MT - 1);
; #pragma unroll
;       for (int i = 0; i < 4; ++i) nx2[i] = *(const f32x4*)(X + (size_t)rn * 1024 + lane * 4 + i * 256);
;     }
;     ln_row_regs(v, g, bb, lane);
;     if (!final_) {
; #pragma unroll
;       for (int i = 0; i < 4; ++i) {
;         *(f32x4*)(X + (size_t)row * 1024 + lane * 4 + i * 256) = v[i];
;         uint2 o; o.x = pk2(v[i][0], v[i][1]); o.y = pk2(v[i][2], v[i][3]);
;         *(uint2*)(xb + (size_t)row * 1024 + lane * 4 + i * 256) = o;
;       }
.LBB0_117:
	v_pk_add_f32 v[76:77], v[60:61], v[32:33]
	v_add_f32_e32 v31, v24, v25
	v_add_f32_e32 v2, v76, v77
	v_pk_add_f32 v[76:77], v[58:59], v[28:29]
	v_add_f32_e32 v67, 0, v2
	v_pk_add_f32 v[76:77], v[76:77], v[76:77] op_sel_hi:[0,1]
	v_add_f32_e32 v63, v26, v27
	v_mov_b32_e32 v65, v77
	v_pk_add_f32 v[30:31], v[30:31], v[62:63]
	v_pk_add_f32 v[62:63], v[64:65], v[66:67]
	s_waitcnt vmcnt(8)
	v_mov_b64_e32 v[36:37], v[10:11]
	v_pk_add_f32 v[30:31], v[30:31], v[62:63]
	v_add_u32_e32 v74, s25, v50
	v_add_f32_e32 v2, v30, v31
	ds_bpermute_b32 v30, v68, v2
	v_mov_b64_e32 v[34:35], v[8:9]
	v_min_i32_e32 v8, 0x427f, v74
	v_ashrrev_i32_e32 v9, 31, v8
	v_lshlrev_b64 v[8:9], 12, v[8:9]
	s_waitcnt lgkmcnt(0)
	v_add_f32_e32 v2, v2, v30
	ds_bpermute_b32 v30, v69, v2
	v_lshl_add_u64 v[8:9], v[0:1], 0, v[8:9]
	global_load_dwordx4 v[38:41], v[8:9], off
	global_load_dwordx4 v[42:45], v[8:9], off offset:1024
	global_load_dwordx4 v[46:49], v[8:9], off offset:2048
	s_nop 0
	global_load_dwordx4 v[8:11], v[8:9], off offset:3072
	s_waitcnt lgkmcnt(0)
	v_add_f32_e32 v2, v2, v30
	ds_bpermute_b32 v30, v70, v2
	s_waitcnt lgkmcnt(0)
	v_add_f32_e32 v2, v2, v30
	ds_bpermute_b32 v30, v71, v2
	s_waitcnt lgkmcnt(0)
	v_add_f32_e32 v2, v2, v30
	ds_bpermute_b32 v30, v72, v2
	s_waitcnt lgkmcnt(0)
	v_add_f32_e32 v2, v2, v30
	ds_bpermute_b32 v30, v73, v2
	s_waitcnt lgkmcnt(0)
	v_add_f32_e32 v51, v2, v30
	v_fmac_f32_e32 v60, 0xba800000, v51
	v_fmac_f32_e32 v33, 0xba800000, v51
	v_fmac_f32_e32 v61, 0xba800000, v51
	v_fmac_f32_e32 v32, 0xba800000, v51
	v_mov_b32_e32 v62, v61
	v_mov_b32_e32 v63, v33
	v_mov_b32_e32 v33, v60
	v_pk_mul_f32 v[30:31], v[62:63], v[62:63]
	v_pk_mul_f32 v[60:61], v[32:33], v[32:33]
	v_fmac_f32_e32 v58, 0xba800000, v51
	v_pk_mov_b32 v[64:65], v[60:61], v[30:31] op_sel:[1,0]
	v_mov_b32_e32 v61, v31
	v_pk_add_f32 v[30:31], v[64:65], v[60:61]
	v_fmac_f32_e32 v29, 0xba800000, v51
	v_fmac_f32_e32 v59, 0xba800000, v51
	v_pk_add_f32 v[60:61], v[30:31], v[30:31] op_sel_hi:[0,1]
	v_fmac_f32_e32 v28, 0xba800000, v51
	v_mov_b32_e32 v30, v59
	v_mov_b32_e32 v31, v29
	v_mov_b32_e32 v29, v58
	v_pk_mul_f32 v[64:65], v[30:31], v[30:31]
	v_pk_mul_f32 v[58:59], v[28:29], v[28:29]
	v_fmac_f32_e32 v24, 0xba800000, v51
	v_pk_mov_b32 v[66:67], v[58:59], v[64:65] op_sel:[1,0]
	v_mov_b32_e32 v59, v65
	v_fmac_f32_e32 v25, 0xba800000, v51
	v_fmac_f32_e32 v26, 0xba800000, v51
	v_mul_f32_e32 v2, v24, v24
	v_pk_add_f32 v[58:59], v[66:67], v[58:59]
	v_fmac_f32_e32 v27, 0xba800000, v51
	v_pk_fma_f32 v[64:65], v[24:25], v[24:25], v[2:3] op_sel_hi:[1,1,0]
	v_mul_f32_e32 v2, v26, v26
	v_pk_add_f32 v[58:59], v[58:59], v[58:59] op_sel_hi:[0,1]
	v_pk_fma_f32 v[66:67], v[26:27], v[26:27], v[2:3] op_sel_hi:[1,1,0]
	v_fmamk_f32 v23, v51, 0xba800000, v23
	v_fmamk_f32 v22, v51, 0xba800000, v22
	v_fmamk_f32 v21, v51, 0xba800000, v21
	v_fmac_f32_e32 v20, 0xba800000, v51
	v_mul_f32_e32 v64, v20, v20
	v_mul_f32_e32 v66, v21, v21
	v_mul_f32_e32 v60, v22, v22
	v_mul_f32_e32 v58, v23, v23
	v_pk_add_f32 v[64:65], v[64:65], v[66:67]
	v_pk_add_f32 v[58:59], v[60:61], v[58:59]
	s_nop 0
	v_pk_add_f32 v[58:59], v[64:65], v[58:59]
	s_nop 0
	v_add_f32_e32 v2, v58, v59
	ds_bpermute_b32 v51, v68, v2
	s_waitcnt lgkmcnt(0)
	v_add_f32_e32 v2, v2, v51
	ds_bpermute_b32 v51, v69, v2
	s_waitcnt lgkmcnt(0)
	v_add_f32_e32 v2, v2, v51
	ds_bpermute_b32 v51, v70, v2
	s_waitcnt lgkmcnt(0)
	v_add_f32_e32 v2, v2, v51
	ds_bpermute_b32 v51, v71, v2
	s_waitcnt lgkmcnt(0)
	v_add_f32_e32 v2, v2, v51
	ds_bpermute_b32 v51, v72, v2
	s_waitcnt lgkmcnt(0)
	v_add_f32_e32 v2, v2, v51
	ds_bpermute_b32 v51, v73, v2
	s_waitcnt lgkmcnt(0)
	v_add_f32_e32 v2, v2, v51
	v_fmamk_f32 v2, v2, 0x3a800000, v156
	v_cmp_gt_f32_e32 vcc, s92, v2
	v_mul_f32_e32 v51, 0x4b800000, v2
	s_nop 0
	v_cndmask_b32_e32 v2, v2, v51, vcc
	v_rsq_f32_e32 v2, v2
	s_nop 0
	v_mul_f32_e32 v51, 0x45800000, v2
	v_cndmask_b32_e32 v2, v2, v51, vcc
	v_pk_mul_f32 v[32:33], v[32:33], v[2:3] op_sel_hi:[1,0]
	v_pk_mul_f32 v[62:63], v[62:63], v[2:3] op_sel_hi:[1,0]
	v_pk_mul_f32 v[28:29], v[28:29], v[2:3] op_sel_hi:[1,0]
	v_pk_mul_f32 v[30:31], v[30:31], v[2:3] op_sel_hi:[1,0]
	v_pk_mul_f32 v[24:25], v[24:25], v[2:3] op_sel_hi:[1,0]
	v_pk_mul_f32 v[26:27], v[26:27], v[2:3] op_sel_hi:[1,0]
	v_ashrrev_i32_e32 v51, 31, v50
	v_pk_mul_f32 v[20:21], v[20:21], v[2:3] op_sel_hi:[1,0]
	v_pk_mul_f32 v[22:23], v[22:23], v[2:3] op_sel_hi:[1,0]
	s_waitcnt vmcnt(0)
	v_pk_fma_f32 v[60:61], v[186:187], v[62:63], v[212:213]
	v_pk_fma_f32 v[58:59], v[184:185], v[32:33], v[210:211]
	v_lshlrev_b64 v[32:33], 12, v[50:51]
	v_lshl_add_u64 v[32:33], v[0:1], 0, v[32:33]
	v_lshlrev_b64 v[50:51], 11, v[50:51]
	v_lshl_add_u64 v[50:51], v[56:57], 0, v[50:51]
	v_mov_b32_e32 v66, v37
	s_waitcnt vmcnt(0)
	v_pk_fma_f32 v[30:31], v[190:191], v[30:31], v[216:217]
	v_pk_fma_f32 v[28:29], v[188:189], v[28:29], v[214:215]
	s_waitcnt vmcnt(0)
	v_pk_fma_f32 v[26:27], v[194:195], v[26:27], v[220:221]
	v_pk_fma_f32 v[24:25], v[192:193], v[24:25], v[218:219]
	s_waitcnt vmcnt(0)
	v_pk_fma_f32 v[22:23], v[198:199], v[22:23], v[224:225]
	global_store_dwordx4 v[32:33], v[58:61], off
	v_pk_fma_f32 v[20:21], v[196:197], v[20:21], v[222:223]
	v_mov_b32_e32 v62, v35
	v_cvt_pk_bf16_f32 v58, v58, v59
	v_cvt_pk_bf16_f32 v59, v60, v61
	global_store_dwordx2 v[50:51], v[58:59], off
	global_store_dwordx4 v[32:33], v[28:31], off offset:1024
	v_mov_b32_e32 v60, v17
	v_mov_b32_e32 v61, v18
	v_cvt_pk_bf16_f32 v28, v28, v29
	v_cvt_pk_bf16_f32 v29, v30, v31
	global_store_dwordx2 v[50:51], v[28:29], off offset:512
	global_store_dwordx4 v[32:33], v[24:27], off offset:2048
	v_mov_b32_e32 v28, v12
	v_mov_b32_e32 v58, v13
	v_cvt_pk_bf16_f32 v24, v24, v25
	v_cvt_pk_bf16_f32 v25, v26, v27
	global_store_dwordx2 v[50:51], v[24:25], off offset:1024
	global_store_dwordx4 v[32:33], v[20:23], off offset:3072
	v_mov_b32_e32 v32, v16
	v_mov_b32_e32 v33, v19
	v_cvt_pk_bf16_f32 v20, v20, v21
	v_cvt_pk_bf16_f32 v21, v22, v23
	global_store_dwordx2 v[50:51], v[20:21], off offset:1536
	v_subrev_u32_e32 v50, s24, v74
	v_mov_b32_e32 v59, v14
	v_mov_b32_e32 v29, v15
	v_mov_b32_e32 v24, v4
	v_mov_b32_e32 v25, v5
	v_mov_b32_e32 v26, v6
	v_mov_b32_e32 v27, v7
	v_cmp_lt_i32_e32 vcc, s23, v50
	v_mov_b64_e32 v[4:5], v[46:47]
	v_mov_b64_e32 v[12:13], v[42:43]
	v_mov_b64_e32 v[16:17], v[38:39]
	v_mov_b64_e32 v[20:21], v[34:35]
	s_or_b64 s[34:35], vcc, s[34:35]
	v_mov_b64_e32 v[6:7], v[48:49]
	v_mov_b64_e32 v[14:15], v[44:45]
	v_mov_b64_e32 v[18:19], v[40:41]
	v_mov_b64_e32 v[22:23], v[36:37]
	v_mov_b32_e32 v30, v34
	v_mov_b32_e32 v64, v36
	s_andn2_b64 exec, exec, s[34:35]
	s_cbranch_execnz .LBB0_117

;   __device__ __forceinline__ unsigned char* W() const { return (unsigned char*)(GAS unsigned char*)ws; }
; __device__ __forceinline__ void ln_row_regs(f32x4 (&v)[4], const float* g, const float* bb, int lane) {
;     ...
;     const f32x4 gg = *(const f32x4*)(g + lane * 4 + i * 256), b4 = *(const f32x4*)(bb + lane * 4 + i * 256);
; __device__ __forceinline__ void ln_phase(const Params& p, const float* g, const float* bb, bf16_t* xb, int final_, int bid, int nb, const int tid) {
;   const int lane = tid & 63, wv = tid >> 6;
;   float* X = (float*)(p.W() + OFF_X);
;   f32x4 nx[4], nx2[4];
;   {
;     const int r0 = min(bid * 4 + wv, MT - 1), r1 = min(bid * 4 + wv + nb * 4, MT - 1);
; #pragma unroll
;     for (int i = 0; i < 4; ++i) nx[i] = *(const f32x4*)(X + (size_t)r0 * 1024 + lane * 4 + i * 256);
; #pragma unroll
;     for (int i = 0; i < 4; ++i) nx2[i] = *(const f32x4*)(X + (size_t)r1 * 1024 + lane * 4 + i * 256);
;   }
.LBB0_626:
	s_and_b64 vcc, exec, s[2:3]
	s_cbranch_vccz .LBB0_643
	v_ashrrev_i32_e32 v0, 6, v130
	v_readlane_b32 s2, v254, 61
	s_nop 1
	v_lshl_add_u32 v0, s2, 2, v0
	s_movk_i32 s2, 0x4280
	v_cmp_gt_i32_e32 vcc, s2, v0
	s_and_saveexec_b64 s[2:3], vcc
	s_cbranch_execz .LBB0_642
	v_lshlrev_b32_e32 v1, 2, v130
	s_lshl_b32 s23, s0, 2
	s_waitcnt vmcnt(4)
	v_and_b32_e32 v24, 0xfc, v1
	v_ashrrev_i32_e32 v1, 31, v0
	s_waitcnt vmcnt(2)
	v_lshlrev_b64 v[4:5], 12, v[0:1]
	v_add_u32_e32 v1, s23, v0
	s_waitcnt vmcnt(1)
	v_min_i32_e32 v8, 0x427f, v1
	v_readlane_b32 s26, v253, 25
	v_ashrrev_i32_e32 v9, 31, v8
	v_readlane_b32 s27, v253, 26
	v_lshlrev_b64 v[8:9], 12, v[8:9]
	v_lshlrev_b32_e32 v2, 2, v24
	v_lshl_add_u64 v[4:5], s[26:27], 0, v[4:5]
	v_lshl_add_u64 v[8:9], s[26:27], 0, v[8:9]
	v_lshl_add_u64 v[4:5], v[4:5], 0, v[2:3]
	v_lshl_add_u64 v[20:21], v[8:9], 0, v[2:3]
	global_load_dwordx4 v[44:47], v[4:5], off
	global_load_dwordx4 v[40:43], v[4:5], off offset:1024
	global_load_dwordx4 v[36:39], v[4:5], off offset:2048
	s_nop 0
	global_load_dwordx4 v[4:7], v[4:5], off offset:3072
	s_nop 0
	global_load_dwordx4 v[8:11], v[20:21], off offset:3072
	global_load_dwordx4 v[12:15], v[20:21], off offset:2048
	global_load_dwordx4 v[16:19], v[20:21], off offset:1024
	s_nop 0
	global_load_dwordx4 v[20:23], v[20:21], off
	v_and_b32_e32 v1, 64, v157
	v_add_u32_e32 v1, 64, v1
	v_xor_b32_e32 v25, 32, v157
	v_cmp_lt_i32_e32 vcc, v25, v1
	s_sub_i32 s24, s64, 17
	s_cmp_gt_u32 s24, -9
	v_cndmask_b32_e32 v25, v157, v25, vcc
	v_lshlrev_b32_e32 v70, 2, v25
	v_xor_b32_e32 v25, 16, v157
	v_cmp_lt_i32_e32 vcc, v25, v1
	s_cselect_b64 s[34:35], -1, 0
	s_lshl_b32 s24, s66, 10
	v_cndmask_b32_e32 v25, v157, v25, vcc
	v_lshlrev_b32_e32 v71, 2, v25
	v_xor_b32_e32 v25, 8, v157
	v_cmp_lt_i32_e32 vcc, v25, v1
	s_ashr_i32 s25, s24, 31
	v_readlane_b32 s36, v254, 37
	v_cndmask_b32_e32 v25, v157, v25, vcc
	v_lshlrev_b32_e32 v72, 2, v25
	v_xor_b32_e32 v25, 4, v157
	v_cmp_lt_i32_e32 vcc, v25, v1
	s_lshl_b64 s[24:25], s[24:25], 2
	v_readlane_b32 s50, v254, 51
	v_cndmask_b32_e32 v25, v157, v25, vcc
	v_lshlrev_b32_e32 v73, 2, v25
	v_xor_b32_e32 v25, 2, v157
	v_readlane_b32 s37, v254, 38
	v_readlane_b32 s51, v254, 52
	s_add_u32 s36, s50, s24
	v_cmp_lt_i32_e32 vcc, v25, v1
	v_readlane_b32 s38, v254, 39
	v_readlane_b32 s48, v254, 49
	s_addc_u32 s37, s51, s25
	v_cndmask_b32_e32 v25, v157, v25, vcc
	v_readlane_b32 s39, v254, 40
	v_readlane_b32 s49, v254, 50
	s_add_u32 s38, s48, s24
	v_lshlrev_b32_e32 v74, 2, v25
	v_xor_b32_e32 v25, 1, v157
	s_addc_u32 s39, s49, s25
	v_cmp_lt_i32_e32 vcc, v25, v1
	v_lshl_add_u64 v[56:57], s[26:27], 0, v[2:3]
	v_lshl_add_u64 v[58:59], s[38:39], 0, v[2:3]
	v_cndmask_b32_e32 v1, v157, v25, vcc
	v_lshl_add_u64 v[60:61], s[36:37], 0, v[2:3]
	v_lshlrev_b32_e32 v2, 1, v24
	s_lshl_b32 s24, s0, 3
	v_lshlrev_b32_e32 v75, 2, v1
	v_lshl_add_u64 v[62:63], s[72:73], 0, v[2:3]
	s_mov_b64 s[36:37], 0
	s_waitcnt vmcnt(8)
	v_lshlrev_b32_e32 v64, 2, v24
	v_readlane_b32 s40, v254, 41
	v_readlane_b32 s41, v254, 42
	v_readlane_b32 s42, v254, 43
	v_readlane_b32 s43, v254, 44
	v_readlane_b32 s44, v254, 45
	v_readlane_b32 s45, v254, 46
	v_readlane_b32 s46, v254, 47
	v_readlane_b32 s47, v254, 48
	s_waitcnt vmcnt(7)
	v_mov_b32_e32 v50, v45
	v_mov_b32_e32 v51, v46
	v_mov_b32_e32 v45, v47
	s_waitcnt vmcnt(6)
	v_mov_b32_e32 v52, v41
	v_mov_b32_e32 v53, v42
	v_mov_b32_e32 v41, v43
	s_waitcnt vmcnt(4)
	v_mov_b32_e32 v66, v4
	v_mov_b32_e32 v68, v5
	v_mov_b32_e32 v42, v6
	v_mov_b32_e32 v54, v7
	global_load_dwordx4 v[184:187], v[58:59], off
	global_load_dwordx4 v[188:191], v[58:59], off offset:1024
	global_load_dwordx4 v[192:195], v[58:59], off offset:2048
	global_load_dwordx4 v[196:199], v[58:59], off offset:3072
	global_load_dwordx4 v[210:213], v[60:61], off
	global_load_dwordx4 v[214:217], v[60:61], off offset:1024
	global_load_dwordx4 v[218:221], v[60:61], off offset:2048
	global_load_dwordx4 v[222:225], v[60:61], off offset:3072
	s_branch .LBB0_630

;   __device__ __forceinline__ float* O() const { return (float*)(GAS float*)out; }
; __device__ __forceinline__ unsigned pk2(float lo, float hi) { const f32x2_t v = {lo, hi}; const bf16x2_t b = __builtin_convertvector(v, bf16x2_t); return __builtin_bit_cast(unsigned, b); }
; __device__ __forceinline__ void ln_row_regs(f32x4 (&v)[4], const float* g, const float* bb, int lane) {
;   float s = 0.f;
; #pragma unroll
;   for (int i = 0; i < 4; ++i) s += (v[i][0] + v[i][1]) + (v[i][2] + v[i][3]);
;   const float mu = wave_sum(s) * (1.0f / 1024.0f);
;   float q = 0.f;
; #pragma unroll
;   for (int i = 0; i < 4; ++i) { const f32x4 d = v[i] - mu; q += (d[0] * d[0] + d[1] * d[1]) + (d[2] * d[2] + d[3] * d[3]); }
;   const float rs = rsqrtf(wave_sum(q) * (1.0f / 1024.0f) + 1e-5f);
; #pragma unroll
;   for (int i = 0; i < 4; ++i) {
;     const f32x4 gg = *(const f32x4*)(g + lane * 4 + i * 256), b4 = *(const f32x4*)(bb + lane * 4 + i * 256);
;     v[i] = (v[i] - mu) * rs * gg + b4;
;   }
; __device__ __forceinline__ void ln_phase(const Params& p, const float* g, const float* bb, bf16_t* xb, int final_, int bid, int nb, const int tid) {
;     ...
;   for (int row = bid * 4 + wv; row < MT; row += nb * 4) {
;     f32x4 v[4];
; #pragma unroll
;     for (int i = 0; i < 4; ++i) { v[i] = nx[i]; nx[i] = nx2[i]; }
;     {
;       const int rn = min(row + nb * 8, MT - 1);
; #pragma unroll
;       for (int i = 0; i < 4; ++i) nx2[i] = *(const f32x4*)(X + (size_t)rn * 1024 + lane * 4 + i * 256);
;     }
;     ln_row_regs(v, g, bb, lane);
;     if (!final_) {
; #pragma unroll
;       for (int i = 0; i < 4; ++i) {
;         *(f32x4*)(X + (size_t)row * 1024 + lane * 4 + i * 256) = v[i];
;         uint2 o; o.x = pk2(v[i][0], v[i][1]); o.y = pk2(v[i][2], v[i][3]);
;         *(uint2*)(xb + (size_t)row * 1024 + lane * 4 + i * 256) = o;
;       }
;     } else {
;       float* dst = nullptr;
;       if (row < MP) { const int b = row / TPR, t = row % TPR; if (t >= 16) dst = p.O() + O_YP + ((size_t)b * 2048 + (t - 16)) * 1024; }
;       else dst = p.O() + O_YS + (size_t)(row - MP) * 1024;
;       if (dst) {
; #pragma unroll
;         for (int i = 0; i < 4; ++i) *(f32x4*)(dst + lane * 4 + i * 256) = v[i];
;       }
;     }
.LBB0_630:
	v_pk_add_f32 v[78:79], v[50:51], v[44:45]
	v_add_f32_e32 v67, v36, v37
	v_add_f32_e32 v1, v78, v79
	v_pk_add_f32 v[78:79], v[52:53], v[40:41]
	v_add_f32_e32 v55, 0, v1
	v_pk_add_f32 v[78:79], v[78:79], v[78:79] op_sel_hi:[0,1]
	v_add_f32_e32 v69, v38, v39
	v_mov_b32_e32 v43, v79
	v_pk_add_f32 v[66:67], v[66:67], v[68:69]
	v_pk_add_f32 v[42:43], v[42:43], v[54:55]
	v_mov_b64_e32 v[48:49], v[6:7]
	v_pk_add_f32 v[42:43], v[66:67], v[42:43]
	v_mov_b64_e32 v[46:47], v[4:5]
	v_add_f32_e32 v1, v42, v43
	ds_bpermute_b32 v2, v70, v1
	s_waitcnt vmcnt(8)
	v_mov_b64_e32 v[4:5], v[8:9]
	v_add_u32_e32 v76, s24, v0
	v_mov_b64_e32 v[6:7], v[10:11]
	v_min_i32_e32 v8, 0x427f, v76
	s_waitcnt lgkmcnt(0)
	v_add_f32_e32 v1, v1, v2
	ds_bpermute_b32 v2, v71, v1
	v_ashrrev_i32_e32 v9, 31, v8
	v_lshlrev_b64 v[8:9], 12, v[8:9]
	v_lshl_add_u64 v[8:9], v[56:57], 0, v[8:9]
	global_load_dwordx4 v[24:27], v[8:9], off
	global_load_dwordx4 v[28:31], v[8:9], off offset:1024
	global_load_dwordx4 v[32:35], v[8:9], off offset:2048
	s_nop 0
	global_load_dwordx4 v[8:11], v[8:9], off offset:3072
	s_waitcnt lgkmcnt(0)
	v_add_f32_e32 v1, v1, v2
	ds_bpermute_b32 v2, v72, v1
	s_mov_b64 s[38:39], -1
	s_waitcnt lgkmcnt(0)
	v_add_f32_e32 v1, v1, v2
	ds_bpermute_b32 v2, v73, v1
	s_waitcnt lgkmcnt(0)
	v_add_f32_e32 v1, v1, v2
	ds_bpermute_b32 v2, v74, v1
	s_waitcnt lgkmcnt(0)
	v_add_f32_e32 v1, v1, v2
	ds_bpermute_b32 v2, v75, v1
	s_waitcnt lgkmcnt(0)
	v_add_f32_e32 v1, v1, v2
	v_fmac_f32_e32 v50, 0xba800000, v1
	v_fmac_f32_e32 v45, 0xba800000, v1
	v_fmac_f32_e32 v51, 0xba800000, v1
	v_fmac_f32_e32 v44, 0xba800000, v1
	v_mov_b32_e32 v42, v51
	v_mov_b32_e32 v43, v45
	v_mov_b32_e32 v45, v50
	v_pk_mul_f32 v[54:55], v[42:43], v[42:43]
	v_pk_mul_f32 v[50:51], v[44:45], v[44:45]
	v_fmac_f32_e32 v52, 0xba800000, v1
	v_pk_mov_b32 v[66:67], v[50:51], v[54:55] op_sel:[1,0]
	v_mov_b32_e32 v51, v55
	v_pk_add_f32 v[50:51], v[66:67], v[50:51]
	v_fmac_f32_e32 v41, 0xba800000, v1
	v_fmac_f32_e32 v53, 0xba800000, v1
	v_pk_add_f32 v[54:55], v[50:51], v[50:51] op_sel_hi:[0,1]
	v_fmac_f32_e32 v40, 0xba800000, v1
	v_mov_b32_e32 v50, v53
	v_mov_b32_e32 v51, v41
	v_mov_b32_e32 v41, v52
	v_pk_mul_f32 v[66:67], v[50:51], v[50:51]
	v_pk_mul_f32 v[52:53], v[40:41], v[40:41]
	v_fmac_f32_e32 v36, 0xba800000, v1
	v_pk_mov_b32 v[68:69], v[52:53], v[66:67] op_sel:[1,0]
	v_mov_b32_e32 v53, v67
	v_fmac_f32_e32 v37, 0xba800000, v1
	v_fmac_f32_e32 v38, 0xba800000, v1
	v_mul_f32_e32 v2, v36, v36
	v_pk_add_f32 v[52:53], v[68:69], v[52:53]
	v_fmac_f32_e32 v39, 0xba800000, v1
	v_pk_fma_f32 v[68:69], v[36:37], v[36:37], v[2:3] op_sel_hi:[1,1,0]
	v_mul_f32_e32 v2, v38, v38
	v_pk_add_f32 v[66:67], v[52:53], v[52:53] op_sel_hi:[0,1]
	v_pk_fma_f32 v[78:79], v[38:39], v[38:39], v[2:3] op_sel_hi:[1,1,0]
	v_fmamk_f32 v53, v1, 0xba800000, v49
	v_fmamk_f32 v52, v1, 0xba800000, v48
	v_fmamk_f32 v47, v1, 0xba800000, v47
	v_fmac_f32_e32 v46, 0xba800000, v1
	v_mul_f32_e32 v68, v46, v46
	v_mul_f32_e32 v78, v47, v47
	v_mul_f32_e32 v54, v52, v52
	v_mul_f32_e32 v66, v53, v53
	v_pk_add_f32 v[48:49], v[68:69], v[78:79]
	v_pk_add_f32 v[54:55], v[54:55], v[66:67]
	v_pk_add_f32 v[48:49], v[48:49], v[54:55]
	s_nop 0
	v_add_f32_e32 v1, v48, v49
	ds_bpermute_b32 v2, v70, v1
	s_waitcnt lgkmcnt(0)
	v_add_f32_e32 v1, v1, v2
	ds_bpermute_b32 v2, v71, v1
	s_waitcnt lgkmcnt(0)
	v_add_f32_e32 v1, v1, v2
	ds_bpermute_b32 v2, v72, v1
	s_waitcnt lgkmcnt(0)
	v_add_f32_e32 v1, v1, v2
	ds_bpermute_b32 v2, v73, v1
	s_waitcnt lgkmcnt(0)
	v_add_f32_e32 v1, v1, v2
	ds_bpermute_b32 v2, v74, v1
	s_waitcnt lgkmcnt(0)
	v_add_f32_e32 v1, v1, v2
	ds_bpermute_b32 v2, v75, v1
	s_waitcnt lgkmcnt(0)
	v_add_f32_e32 v1, v1, v2
	v_fmamk_f32 v1, v1, 0x3a800000, v156
	v_cmp_gt_f32_e32 vcc, s92, v1
	v_mul_f32_e32 v2, 0x4b800000, v1
	s_nop 0
	v_cndmask_b32_e32 v1, v1, v2, vcc
	v_rsq_f32_e32 v1, v1
	s_nop 0
	v_mul_f32_e32 v2, 0x45800000, v1
	v_cndmask_b32_e32 v2, v1, v2, vcc
	v_pk_mul_f32 v[48:49], v[44:45], v[2:3] op_sel_hi:[1,0]
	v_pk_mul_f32 v[42:43], v[42:43], v[2:3] op_sel_hi:[1,0]
	v_pk_mul_f32 v[40:41], v[40:41], v[2:3] op_sel_hi:[1,0]
	v_pk_mul_f32 v[36:37], v[36:37], v[2:3] op_sel_hi:[1,0]
	v_pk_mul_f32 v[38:39], v[38:39], v[2:3] op_sel_hi:[1,0]
	s_and_b64 vcc, exec, s[34:35]
	s_waitcnt vmcnt(0)
	v_pk_fma_f32 v[44:45], v[186:187], v[42:43], v[212:213]
	v_pk_fma_f32 v[42:43], v[184:185], v[48:49], v[210:211]
	v_pk_mul_f32 v[48:49], v[50:51], v[2:3] op_sel_hi:[1,0]
	s_waitcnt vmcnt(0)
	v_pk_fma_f32 v[50:51], v[190:191], v[48:49], v[216:217]
	v_pk_fma_f32 v[48:49], v[188:189], v[40:41], v[214:215]
	v_pk_mul_f32 v[40:41], v[46:47], v[2:3] op_sel_hi:[1,0]
	v_pk_mul_f32 v[46:47], v[52:53], v[2:3] op_sel_hi:[1,0]
	s_waitcnt vmcnt(0)
	v_pk_fma_f32 v[38:39], v[194:195], v[38:39], v[220:221]
	v_pk_fma_f32 v[36:37], v[192:193], v[36:37], v[218:219]
	s_waitcnt vmcnt(0)
	v_pk_fma_f32 v[54:55], v[198:199], v[46:47], v[224:225]
	v_pk_fma_f32 v[52:53], v[196:197], v[40:41], v[222:223]
	s_cbranch_vccz .LBB0_636
	s_movk_i32 s25, 0x407f
	v_cmp_lt_i32_e32 vcc, s25, v0
	s_and_saveexec_b64 s[26:27], vcc
	s_xor_b64 s[38:39], exec, s[26:27]
	s_cbranch_execz .LBB0_638
	v_add_u32_e32 v2, 0xffffbf80, v0
	v_readlane_b32 s26, v253, 57
	v_lshlrev_b64 v[40:41], 12, v[2:3]
	v_readlane_b32 s27, v253, 58
	s_nop 1
	v_lshl_add_u64 v[40:41], s[26:27], 0, v[40:41]
	s_andn2_saveexec_b64 s[38:39], s[38:39]
	s_cbranch_execnz .LBB0_639
